# qkprep row loop unrolled x3 with 3-row-deep q/k prefetch (in-order vmcnt no longer behind previous row stores)
# baseline (speedup 1.0000x reference)
.LBB0_385:
	s_or_b64 exec, exec, s[10:11]
	v_ashrrev_i32_e32 v1, 6, v35
	v_readlane_b32 s6, v253, 0
	s_waitcnt lgkmcnt(0)
	s_barrier
	v_add_u32_e32 v34, s6, v1
	s_movk_i32 s6, 0x4400
	v_cmp_gt_i32_e32 vcc, s6, v34
	s_and_saveexec_b64 s[10:11], vcc
	s_cbranch_execz .LBB0_392
	s_load_dwordx4 s[40:43], s[12:13], 0x50
	v_readlane_b32 s14, v255, 14
	v_and_b32_e32 v1, 3, v35
	s_lshl_b32 s6, s14, 6
	v_lshl_or_b32 v2, v1, 4, s6
	v_mov_b32_e32 v3, v0
	v_lshlrev_b64 v[18:19], 2, v[2:3]
	s_waitcnt lgkmcnt(0)
	v_lshl_add_u64 v[14:15], s[42:43], 0, v[18:19]
	v_lshl_add_u64 v[30:31], s[40:41], 0, v[18:19]
	global_load_dwordx4 v[2:5], v[14:15], off offset:48
	global_load_dwordx4 v[6:9], v[14:15], off offset:32
	global_load_dwordx4 v[10:13], v[14:15], off offset:16
	s_nop 0
	global_load_dwordx4 v[14:17], v[14:15], off
	s_nop 0
	global_load_dwordx4 v[18:21], v[30:31], off offset:48
	global_load_dwordx4 v[22:25], v[30:31], off offset:32
	global_load_dwordx4 v[26:29], v[30:31], off offset:16
	s_nop 0
	global_load_dwordx4 v[30:33], v[30:31], off
	s_load_dwordx2 s[12:13], s[12:13], 0xb0
	v_cmp_lt_i32_e64 s[40:41], v231, v225
	v_cmp_gt_u32_e32 vcc, 2, v1
	v_mov_b32_e32 v37, v0
	v_cndmask_b32_e64 v1, v223, v231, s[40:41]
	v_cmp_lt_i32_e64 s[40:41], v230, v225
	v_lshlrev_b32_e32 v1, 2, v1
	v_readlane_b32 s15, v255, 15
	v_cndmask_b32_e64 v36, v223, v230, s[40:41]
	v_lshlrev_b32_e32 v60, 2, v36
	v_and_b32_e32 v36, 1, v35
	v_lshlrev_b32_e32 v35, 5, v35
	v_cmp_eq_u32_e64 s[40:41], 0, v36
	v_and_b32_e32 v36, 0x7e0, v35
	s_waitcnt lgkmcnt(0)
	v_lshl_add_u64 v[38:39], s[12:13], 0, v[36:37]
	s_mov_b64 s[12:13], 0x14610000
	v_lshl_add_u64 v[36:37], v[38:39], 0, s[12:13]
	s_mov_b64 s[12:13], 0x16810000
	v_lshl_add_u64 v[38:39], v[38:39], 0, s[12:13]
	s_mov_b64 s[12:13], 0
	v_ashrrev_i32_e32 v35, 31, v34
	v_lshlrev_b64 v[40:41], 11, v[34:35]
	v_lshl_add_u64 v[96:97], v[36:37], 0, v[40:41]
	v_lshl_add_u64 v[98:99], v[38:39], 0, v[40:41]
	global_load_dwordx4 v[100:103], v[96:97], off offset:16
	global_load_dwordx4 v[104:107], v[96:97], off
	global_load_dwordx4 v[108:111], v[98:99], off offset:16
	global_load_dwordx4 v[112:115], v[98:99], off
	v_readlane_b32 s100, v254, 47
	s_mov_b32 s101, 0
	s_lshl_b32 s100, s100, 11
	v_lshl_add_u64 v[96:97], s[100:101], 0, v[96:97]
	v_lshl_add_u64 v[98:99], s[100:101], 0, v[98:99]
	global_load_dwordx4 v[116:119], v[96:97], off offset:16
	global_load_dwordx4 v[120:123], v[96:97], off
	global_load_dwordx4 v[124:127], v[98:99], off offset:16
	global_load_dwordx4 v[128:131], v[98:99], off
	v_lshl_add_u64 v[96:97], s[100:101], 0, v[96:97]
	v_lshl_add_u64 v[98:99], s[100:101], 0, v[98:99]
	global_load_dwordx4 v[132:135], v[96:97], off offset:16
	global_load_dwordx4 v[136:139], v[96:97], off
	global_load_dwordx4 v[140:143], v[98:99], off offset:16
	global_load_dwordx4 v[144:147], v[98:99], off
	s_mul_i32 s100, s100, 3
	s_waitcnt vmcnt(0)
	s_branch .LBB0_388
.LBB0_388:
	v_ashrrev_i32_e32 v35, 31, v34
	v_lshlrev_b64 v[40:41], 11, v[34:35]
	v_lshl_add_u64 v[42:43], v[36:37], 0, v[40:41]
	s_waitcnt vmcnt(22)
	v_mov_b32_e32 v44, v100
	v_mov_b32_e32 v45, v101
	v_mov_b32_e32 v46, v102
	v_mov_b32_e32 v47, v103
	v_mov_b32_e32 v48, v104
	v_mov_b32_e32 v49, v105
	v_mov_b32_e32 v50, v106
	v_mov_b32_e32 v51, v107
	v_lshl_add_u64 v[96:97], s[100:101], 0, v[42:43]
	global_load_dwordx4 v[100:103], v[96:97], off offset:16
	global_load_dwordx4 v[104:107], v[96:97], off
	s_mov_b32 s6, 0x78787879
	v_mul_hi_i32 v35, v34, s6
	s_movk_i32 s6, 0xff
	v_lshlrev_b32_e32 v58, 16, v44
	v_lshlrev_b32_e32 v54, 16, v48
	v_and_b32_e32 v55, 0xffff0000, v48
	v_lshlrev_b32_e32 v48, 16, v49
	v_and_b32_e32 v49, 0xffff0000, v49
	v_pk_mul_f32 v[64:65], v[54:55], v[54:55]
	v_pk_mul_f32 v[66:67], v[48:49], v[48:49]
	v_add_f32_e32 v61, v64, v65
	v_lshlrev_b32_e32 v56, 16, v50
	v_and_b32_e32 v57, 0xffff0000, v50
	v_add_f32_e32 v61, v66, v61
	v_pk_mul_f32 v[68:69], v[56:57], v[56:57]
	v_add_f32_e32 v61, v67, v61
	v_lshlrev_b32_e32 v50, 16, v51
	v_and_b32_e32 v51, 0xffff0000, v51
	v_add_f32_e32 v61, v68, v61
	v_pk_mul_f32 v[70:71], v[50:51], v[50:51]
	v_add_f32_e32 v61, v69, v61
	v_and_b32_e32 v59, 0xffff0000, v44
	v_add_f32_e32 v61, v70, v61
	v_pk_mul_f32 v[72:73], v[58:59], v[58:59]
	v_add_f32_e32 v61, v71, v61
	v_lshlrev_b32_e32 v44, 16, v45
	v_and_b32_e32 v45, 0xffff0000, v45
	v_add_f32_e32 v61, v72, v61
	v_pk_mul_f32 v[74:75], v[44:45], v[44:45]
	v_add_f32_e32 v61, v73, v61
	v_lshlrev_b32_e32 v62, 16, v46
	v_and_b32_e32 v63, 0xffff0000, v46
	v_add_f32_e32 v61, v74, v61
	v_pk_mul_f32 v[76:77], v[62:63], v[62:63]
	v_add_f32_e32 v61, v75, v61
	v_and_b32_e32 v52, 0xffff0000, v47
	v_lshlrev_b32_e32 v53, 16, v47
	v_add_f32_e32 v61, v76, v61
	v_pk_mul_f32 v[46:47], v[52:53], v[52:53]
	v_add_f32_e32 v61, v77, v61
	v_add_f32_e32 v47, v47, v61
	v_add_f32_e32 v46, v46, v47
	s_nop 1
	v_mov_b32_dpp v47, v46 quad_perm:[1,0,3,2] row_mask:0xf bank_mask:0xf
	v_lshrrev_b32_e32 v61, 31, v35
	v_ashrrev_i32_e32 v35, 11, v35
	v_add_u32_e32 v35, v35, v61
	v_mul_i32_i24_e32 v35, 0x1100, v35
	v_add_f32_e32 v46, v46, v47
	s_nop 1
	v_mov_b32_dpp v47, v46 quad_perm:[2,3,0,1] row_mask:0xf bank_mask:0xf
	v_sub_u32_e32 v35, v34, v35
	v_add_u32_e32 v61, 0xffffff00, v35
	v_cmp_lt_i32_e64 s[42:43], s6, v35
	v_and_b32_e32 v35, 63, v35
	v_add_f32_e32 v46, v46, v47
	v_fmamk_f32 v46, v46, 0x3c800000, v234
	v_mul_f32_e32 v47, 0x4b800000, v46
	v_cmp_gt_f32_e64 s[44:45], s90, v46
	s_nop 1
	v_cndmask_b32_e64 v46, v46, v47, s[44:45]
	v_rsq_f32_e32 v46, v46
	v_ashrrev_i32_e32 v47, 6, v61
	v_cndmask_b32_e32 v35, v35, v47, vcc
	v_lshlrev_b32_e32 v35, 4, v35
	v_mul_f32_e32 v47, 0x45800000, v46
	v_cndmask_b32_e64 v46, v46, v47, s[44:45]
	v_pk_mul_f32 v[54:55], v[46:47], v[54:55] op_sel_hi:[0,1]
	v_pk_mul_f32 v[48:49], v[46:47], v[48:49] op_sel_hi:[0,1]
	v_pk_mul_f32 v[64:65], v[46:47], v[56:57] op_sel_hi:[0,1]
	v_pk_mul_f32 v[50:51], v[46:47], v[50:51] op_sel_hi:[0,1]
	v_pk_mul_f32 v[66:67], v[46:47], v[58:59] op_sel_hi:[0,1]
	v_pk_mul_f32 v[44:45], v[46:47], v[44:45] op_sel_hi:[0,1]
	v_pk_mul_f32 v[62:63], v[46:47], v[62:63] op_sel_hi:[0,1]
	v_pk_mul_f32 v[68:69], v[46:47], v[52:53] op_sel_hi:[0,1]
	v_pk_mul_f32 v[58:59], v[30:31], v[54:55]
	v_pk_mul_f32 v[56:57], v[32:33], v[48:49]
	v_pk_mul_f32 v[54:55], v[26:27], v[64:65]
	v_pk_mul_f32 v[52:53], v[28:29], v[50:51]
	v_pk_mul_f32 v[50:51], v[22:23], v[66:67]
	v_pk_mul_f32 v[48:49], v[24:25], v[44:45]
	v_pk_mul_f32 v[46:47], v[18:19], v[62:63]
	v_pk_mul_f32 v[44:45], v[20:21], v[68:69] op_sel:[0,1] op_sel_hi:[1,0]
	v_lshl_add_u32 v35, v35, 2, 0
	s_and_saveexec_b64 s[14:15], s[42:43]
	s_cbranch_execz .LBB0_390
	v_mov_b32_dpp v82, v58 quad_perm:[1,0,3,2] row_mask:0xf bank_mask:0xf
	v_mov_b32_dpp v83, v59 quad_perm:[1,0,3,2] row_mask:0xf bank_mask:0xf
	ds_read_b128 v[62:65], v35
	ds_read_b128 v[66:69], v35 offset:16
	ds_read_b128 v[70:73], v35 offset:32
	ds_read_b128 v[74:77], v35 offset:48
	ds_read_b128 v[78:81], v35 offset:4096
	v_mov_b32_dpp v86, v54 quad_perm:[1,0,3,2] row_mask:0xf bank_mask:0xf
	v_mov_b32_dpp v87, v55 quad_perm:[1,0,3,2] row_mask:0xf bank_mask:0xf
	v_mov_b32_dpp v90, v50 quad_perm:[1,0,3,2] row_mask:0xf bank_mask:0xf
	v_mov_b32_dpp v91, v51 quad_perm:[1,0,3,2] row_mask:0xf bank_mask:0xf
	s_waitcnt lgkmcnt(0)
	v_pk_mul_f32 v[82:83], v[78:79], v[82:83]
	v_mov_b32_dpp v78, v56 quad_perm:[1,0,3,2] row_mask:0xf bank_mask:0xf
	v_mov_b32_dpp v79, v57 quad_perm:[1,0,3,2] row_mask:0xf bank_mask:0xf
	v_mov_b32_dpp v94, v46 quad_perm:[1,0,3,2] row_mask:0xf bank_mask:0xf
	v_mov_b32_dpp v95, v47 quad_perm:[1,0,3,2] row_mask:0xf bank_mask:0xf
	v_cndmask_b32_e64 v83, v83, -v83, s[40:41]
	v_cndmask_b32_e64 v82, v82, -v82, s[40:41]
	v_pk_mul_f32 v[84:85], v[80:81], v[78:79]
	ds_read_b128 v[78:81], v35 offset:4112
	v_cndmask_b32_e64 v85, v85, -v85, s[40:41]
	v_cndmask_b32_e64 v84, v84, -v84, s[40:41]
	v_pk_fma_f32 v[56:57], v[56:57], v[64:65], v[84:85]
	v_pk_fma_f32 v[58:59], v[58:59], v[62:63], v[82:83]
	s_waitcnt lgkmcnt(0)
	v_pk_mul_f32 v[86:87], v[78:79], v[86:87]
	v_mov_b32_dpp v78, v52 quad_perm:[1,0,3,2] row_mask:0xf bank_mask:0xf
	v_mov_b32_dpp v79, v53 quad_perm:[1,0,3,2] row_mask:0xf bank_mask:0xf
	v_cndmask_b32_e64 v87, v87, -v87, s[40:41]
	v_cndmask_b32_e64 v86, v86, -v86, s[40:41]
	v_pk_fma_f32 v[54:55], v[54:55], v[66:67], v[86:87]
	v_pk_mul_f32 v[88:89], v[80:81], v[78:79]
	ds_read_b128 v[78:81], v35 offset:4128
	v_cndmask_b32_e64 v88, v88, -v88, s[40:41]
	v_cndmask_b32_e64 v89, v89, -v89, s[40:41]
	v_pk_fma_f32 v[52:53], v[52:53], v[68:69], v[88:89]
	s_waitcnt lgkmcnt(0)
	v_pk_mul_f32 v[90:91], v[78:79], v[90:91]
	v_mov_b32_dpp v78, v48 quad_perm:[1,0,3,2] row_mask:0xf bank_mask:0xf
	v_mov_b32_dpp v79, v49 quad_perm:[1,0,3,2] row_mask:0xf bank_mask:0xf
	v_cndmask_b32_e64 v90, v90, -v90, s[40:41]
	v_cndmask_b32_e64 v91, v91, -v91, s[40:41]
	v_pk_fma_f32 v[50:51], v[50:51], v[70:71], v[90:91]
	v_pk_mul_f32 v[92:93], v[80:81], v[78:79]
	ds_read_b128 v[78:81], v35 offset:4144
	v_cndmask_b32_e64 v92, v92, -v92, s[40:41]
	v_cndmask_b32_e64 v93, v93, -v93, s[40:41]
	v_pk_fma_f32 v[48:49], v[48:49], v[72:73], v[92:93]
	s_waitcnt lgkmcnt(0)
	v_pk_mul_f32 v[78:79], v[78:79], v[94:95]
	v_mov_b32_dpp v94, v44 quad_perm:[1,0,3,2] row_mask:0xf bank_mask:0xf
	v_mov_b32_dpp v95, v45 quad_perm:[1,0,3,2] row_mask:0xf bank_mask:0xf
	v_cndmask_b32_e64 v78, v78, -v78, s[40:41]
	v_cndmask_b32_e64 v79, v79, -v79, s[40:41]
	v_pk_fma_f32 v[46:47], v[46:47], v[74:75], v[78:79]
	v_pk_mul_f32 v[80:81], v[80:81], v[94:95]
	s_nop 0
	v_cndmask_b32_e64 v80, v80, -v80, s[40:41]
	v_cndmask_b32_e64 v81, v81, -v81, s[40:41]
	v_pk_fma_f32 v[44:45], v[44:45], v[76:77], v[80:81]
.LBB0_390:
	s_or_b64 exec, exec, s[14:15]
	v_mul_f32_e32 v50, 0x3e38aa3b, v50
	v_mul_f32_e32 v47, 0x3e38aa3b, v47
	v_mul_f32_e32 v58, 0x3e38aa3b, v58
	v_mul_f32_e32 v59, 0x3e38aa3b, v59
	v_mul_f32_e32 v56, 0x3e38aa3b, v56
	v_mul_f32_e32 v57, 0x3e38aa3b, v57
	v_mul_f32_e32 v54, 0x3e38aa3b, v54
	v_mul_f32_e32 v55, 0x3e38aa3b, v55
	v_mul_f32_e32 v52, 0x3e38aa3b, v52
	v_mul_f32_e32 v53, 0x3e38aa3b, v53
	v_mul_f32_e32 v51, 0x3e38aa3b, v51
	v_mul_f32_e32 v61, 0x3e38aa3b, v48
	v_mul_f32_e32 v49, 0x3e38aa3b, v49
	v_mul_f32_e32 v62, 0x3e38aa3b, v46
	v_mul_f32_e32 v63, 0x3e38aa3b, v44
	v_mul_f32_e32 v64, 0x3e38aa3b, v45
	s_nop 1
	v_cvt_pk_bf16_f32 v44, v58, v59
	s_nop 1
	v_cvt_pk_bf16_f32 v48, v50, v51
	s_nop 1
	v_cvt_pk_bf16_f32 v45, v56, v57
	s_nop 1
	v_cvt_pk_bf16_f32 v46, v54, v55
	s_nop 1
	v_cvt_pk_bf16_f32 v50, v62, v47
	s_nop 1
	v_cvt_pk_bf16_f32 v47, v52, v53
	s_nop 1
	v_cvt_pk_bf16_f32 v49, v61, v49
	s_nop 1
	v_cvt_pk_bf16_f32 v51, v63, v64
	global_store_dwordx4 v[42:43], v[44:47], off
	global_store_dwordx4 v[42:43], v[48:51], off offset:16
	v_lshl_add_u64 v[40:41], v[38:39], 0, v[40:41]
	s_waitcnt vmcnt(22)
	s_nop 1
	v_mov_b32_e32 v42, v108
	v_mov_b32_e32 v43, v109
	v_mov_b32_e32 v44, v110
	v_mov_b32_e32 v45, v111
	v_mov_b32_e32 v46, v112
	v_mov_b32_e32 v47, v113
	v_mov_b32_e32 v48, v114
	v_mov_b32_e32 v49, v115
	v_lshl_add_u64 v[96:97], s[100:101], 0, v[40:41]
	global_load_dwordx4 v[108:111], v[96:97], off offset:16
	global_load_dwordx4 v[112:115], v[96:97], off
	v_lshlrev_b32_e32 v68, 16, v42
	v_lshlrev_b32_e32 v52, 16, v46
	v_and_b32_e32 v53, 0xffff0000, v46
	v_pk_mul_f32 v[54:55], v[52:53], v[52:53]
	v_lshlrev_b32_e32 v46, 16, v47
	v_and_b32_e32 v47, 0xffff0000, v47
	v_pk_mul_f32 v[58:59], v[46:47], v[46:47]
	v_add_f32_e32 v54, v54, v55
	v_lshlrev_b32_e32 v62, 16, v48
	v_and_b32_e32 v63, 0xffff0000, v48
	v_add_f32_e32 v54, v58, v54
	v_pk_mul_f32 v[64:65], v[62:63], v[62:63]
	v_add_f32_e32 v54, v59, v54
	v_lshlrev_b32_e32 v48, 16, v49
	v_and_b32_e32 v49, 0xffff0000, v49
	v_add_f32_e32 v54, v64, v54
	v_pk_mul_f32 v[66:67], v[48:49], v[48:49]
	v_add_f32_e32 v54, v65, v54
	v_and_b32_e32 v69, 0xffff0000, v42
	v_add_f32_e32 v54, v66, v54
	v_pk_mul_f32 v[70:71], v[68:69], v[68:69]
	v_add_f32_e32 v54, v67, v54
	v_lshlrev_b32_e32 v72, 16, v43
	v_and_b32_e32 v73, 0xffff0000, v43
	v_add_f32_e32 v54, v70, v54
	v_pk_mul_f32 v[42:43], v[72:73], v[72:73]
	v_add_f32_e32 v54, v71, v54
	v_lshlrev_b32_e32 v74, 16, v44
	v_and_b32_e32 v75, 0xffff0000, v44
	v_add_f32_e32 v42, v42, v54
	v_and_b32_e32 v56, 0xffff0000, v45
	v_lshlrev_b32_e32 v57, 16, v45
	v_pk_mul_f32 v[44:45], v[74:75], v[74:75]
	v_add_f32_e32 v42, v43, v42
	v_add_f32_e32 v42, v44, v42
	v_pk_mul_f32 v[50:51], v[56:57], v[56:57]
	v_add_f32_e32 v42, v45, v42
	v_add_f32_e32 v42, v51, v42
	v_add_f32_e32 v42, v50, v42
	s_nop 1
	v_mov_b32_dpp v43, v42 quad_perm:[1,0,3,2] row_mask:0xf bank_mask:0xf
	v_add_f32_e32 v42, v42, v43
	s_nop 1
	v_mov_b32_dpp v43, v42 quad_perm:[2,3,0,1] row_mask:0xf bank_mask:0xf
	v_add_f32_e32 v42, v42, v43
	v_fmamk_f32 v42, v42, 0x3c800000, v234
	v_cmp_gt_f32_e64 s[44:45], s90, v42
	v_mul_f32_e32 v43, 0x4b800000, v42
	s_nop 0
	v_cndmask_b32_e64 v42, v42, v43, s[44:45]
	v_rsq_f32_e32 v42, v42
	s_nop 0
	v_mul_f32_e32 v43, 0x45800000, v42
	v_cndmask_b32_e64 v58, v42, v43, s[44:45]
	v_pk_mul_f32 v[42:43], v[58:59], v[52:53] op_sel_hi:[0,1]
	v_pk_mul_f32 v[44:45], v[58:59], v[46:47] op_sel_hi:[0,1]
	v_pk_mul_f32 v[46:47], v[58:59], v[62:63] op_sel_hi:[0,1]
	v_pk_mul_f32 v[48:49], v[58:59], v[48:49] op_sel_hi:[0,1]
	v_pk_mul_f32 v[50:51], v[58:59], v[68:69] op_sel_hi:[0,1]
	v_pk_mul_f32 v[52:53], v[58:59], v[72:73] op_sel_hi:[0,1]
	v_pk_mul_f32 v[54:55], v[58:59], v[74:75] op_sel_hi:[0,1]
	v_pk_mul_f32 v[56:57], v[58:59], v[56:57] op_sel_hi:[0,1]
	v_pk_mul_f32 v[42:43], v[14:15], v[42:43]
	v_pk_mul_f32 v[44:45], v[16:17], v[44:45]
	v_pk_mul_f32 v[46:47], v[10:11], v[46:47]
	v_pk_mul_f32 v[48:49], v[12:13], v[48:49]
	v_pk_mul_f32 v[50:51], v[6:7], v[50:51]
	v_pk_mul_f32 v[52:53], v[8:9], v[52:53]
	v_pk_mul_f32 v[54:55], v[2:3], v[54:55]
	v_pk_mul_f32 v[56:57], v[4:5], v[56:57] op_sel:[0,1] op_sel_hi:[1,0]
	s_and_saveexec_b64 s[14:15], s[42:43]
	s_cbranch_execz .LBB0_387
	v_mov_b32_dpp v58, v42 quad_perm:[1,0,3,2] row_mask:0xf bank_mask:0xf
	v_mov_b32_dpp v59, v43 quad_perm:[1,0,3,2] row_mask:0xf bank_mask:0xf
	ds_read_b128 v[62:65], v35
	ds_read_b128 v[66:69], v35 offset:16
	ds_read_b128 v[70:73], v35 offset:32
	ds_read_b128 v[74:77], v35 offset:48
	ds_read_b128 v[78:81], v35 offset:4096
	v_mov_b32_dpp v84, v46 quad_perm:[1,0,3,2] row_mask:0xf bank_mask:0xf
	v_mov_b32_dpp v85, v47 quad_perm:[1,0,3,2] row_mask:0xf bank_mask:0xf
	v_mov_b32_dpp v88, v50 quad_perm:[1,0,3,2] row_mask:0xf bank_mask:0xf
	v_mov_b32_dpp v89, v51 quad_perm:[1,0,3,2] row_mask:0xf bank_mask:0xf
	s_waitcnt lgkmcnt(0)
	v_pk_mul_f32 v[58:59], v[78:79], v[58:59]
	v_mov_b32_dpp v78, v44 quad_perm:[1,0,3,2] row_mask:0xf bank_mask:0xf
	v_mov_b32_dpp v79, v45 quad_perm:[1,0,3,2] row_mask:0xf bank_mask:0xf
	v_mov_b32_dpp v92, v54 quad_perm:[1,0,3,2] row_mask:0xf bank_mask:0xf
	v_mov_b32_dpp v93, v55 quad_perm:[1,0,3,2] row_mask:0xf bank_mask:0xf
	v_cndmask_b32_e64 v59, v59, -v59, s[40:41]
	v_cndmask_b32_e64 v58, v58, -v58, s[40:41]
	v_pk_mul_f32 v[82:83], v[80:81], v[78:79]
	ds_read_b128 v[78:81], v35 offset:4112
	v_cndmask_b32_e64 v83, v83, -v83, s[40:41]
	v_cndmask_b32_e64 v82, v82, -v82, s[40:41]
	v_pk_fma_f32 v[44:45], v[44:45], v[64:65], v[82:83]
	v_pk_fma_f32 v[42:43], v[42:43], v[62:63], v[58:59]
	s_waitcnt lgkmcnt(0)
	v_pk_mul_f32 v[84:85], v[78:79], v[84:85]
	v_mov_b32_dpp v78, v48 quad_perm:[1,0,3,2] row_mask:0xf bank_mask:0xf
	v_mov_b32_dpp v79, v49 quad_perm:[1,0,3,2] row_mask:0xf bank_mask:0xf
	v_cndmask_b32_e64 v85, v85, -v85, s[40:41]
	v_cndmask_b32_e64 v84, v84, -v84, s[40:41]
	v_pk_fma_f32 v[46:47], v[46:47], v[66:67], v[84:85]
	v_pk_mul_f32 v[86:87], v[80:81], v[78:79]
	ds_read_b128 v[78:81], v35 offset:4128
	v_cndmask_b32_e64 v86, v86, -v86, s[40:41]
	v_cndmask_b32_e64 v87, v87, -v87, s[40:41]
	v_pk_fma_f32 v[48:49], v[48:49], v[68:69], v[86:87]
	s_waitcnt lgkmcnt(0)
	v_pk_mul_f32 v[88:89], v[78:79], v[88:89]
	v_mov_b32_dpp v78, v52 quad_perm:[1,0,3,2] row_mask:0xf bank_mask:0xf
	v_mov_b32_dpp v79, v53 quad_perm:[1,0,3,2] row_mask:0xf bank_mask:0xf
	v_cndmask_b32_e64 v88, v88, -v88, s[40:41]
	v_cndmask_b32_e64 v89, v89, -v89, s[40:41]
	v_pk_fma_f32 v[50:51], v[50:51], v[70:71], v[88:89]
	v_pk_mul_f32 v[90:91], v[80:81], v[78:79]
	ds_read_b128 v[78:81], v35 offset:4144
	v_cndmask_b32_e64 v90, v90, -v90, s[40:41]
	v_cndmask_b32_e64 v91, v91, -v91, s[40:41]
	v_pk_fma_f32 v[52:53], v[52:53], v[72:73], v[90:91]
	s_waitcnt lgkmcnt(0)
	v_pk_mul_f32 v[78:79], v[78:79], v[92:93]
	v_mov_b32_dpp v92, v56 quad_perm:[1,0,3,2] row_mask:0xf bank_mask:0xf
	v_mov_b32_dpp v93, v57 quad_perm:[1,0,3,2] row_mask:0xf bank_mask:0xf
	v_cndmask_b32_e64 v78, v78, -v78, s[40:41]
	v_cndmask_b32_e64 v79, v79, -v79, s[40:41]
	v_pk_fma_f32 v[54:55], v[54:55], v[74:75], v[78:79]
	v_pk_mul_f32 v[80:81], v[80:81], v[92:93]
	s_nop 0
	v_cndmask_b32_e64 v80, v80, -v80, s[40:41]
	v_cndmask_b32_e64 v81, v81, -v81, s[40:41]
	v_pk_fma_f32 v[56:57], v[56:57], v[76:77], v[80:81]

.Lqk_head_1:
	v_ashrrev_i32_e32 v35, 31, v34
	v_lshlrev_b64 v[40:41], 11, v[34:35]
	v_lshl_add_u64 v[42:43], v[36:37], 0, v[40:41]
	s_waitcnt vmcnt(22)
	v_mov_b32_e32 v44, v116
	v_mov_b32_e32 v45, v117
	v_mov_b32_e32 v46, v118
	v_mov_b32_e32 v47, v119
	v_mov_b32_e32 v48, v120
	v_mov_b32_e32 v49, v121
	v_mov_b32_e32 v50, v122
	v_mov_b32_e32 v51, v123
	v_lshl_add_u64 v[96:97], s[100:101], 0, v[42:43]
	global_load_dwordx4 v[116:119], v[96:97], off offset:16
	global_load_dwordx4 v[120:123], v[96:97], off
	s_mov_b32 s6, 0x78787879
	v_mul_hi_i32 v35, v34, s6
	s_movk_i32 s6, 0xff
	v_lshlrev_b32_e32 v58, 16, v44
	v_lshlrev_b32_e32 v54, 16, v48
	v_and_b32_e32 v55, 0xffff0000, v48
	v_lshlrev_b32_e32 v48, 16, v49
	v_and_b32_e32 v49, 0xffff0000, v49
	v_pk_mul_f32 v[64:65], v[54:55], v[54:55]
	v_pk_mul_f32 v[66:67], v[48:49], v[48:49]
	v_add_f32_e32 v61, v64, v65
	v_lshlrev_b32_e32 v56, 16, v50
	v_and_b32_e32 v57, 0xffff0000, v50
	v_add_f32_e32 v61, v66, v61
	v_pk_mul_f32 v[68:69], v[56:57], v[56:57]
	v_add_f32_e32 v61, v67, v61
	v_lshlrev_b32_e32 v50, 16, v51
	v_and_b32_e32 v51, 0xffff0000, v51
	v_add_f32_e32 v61, v68, v61
	v_pk_mul_f32 v[70:71], v[50:51], v[50:51]
	v_add_f32_e32 v61, v69, v61
	v_and_b32_e32 v59, 0xffff0000, v44
	v_add_f32_e32 v61, v70, v61
	v_pk_mul_f32 v[72:73], v[58:59], v[58:59]
	v_add_f32_e32 v61, v71, v61
	v_lshlrev_b32_e32 v44, 16, v45
	v_and_b32_e32 v45, 0xffff0000, v45
	v_add_f32_e32 v61, v72, v61
	v_pk_mul_f32 v[74:75], v[44:45], v[44:45]
	v_add_f32_e32 v61, v73, v61
	v_lshlrev_b32_e32 v62, 16, v46
	v_and_b32_e32 v63, 0xffff0000, v46
	v_add_f32_e32 v61, v74, v61
	v_pk_mul_f32 v[76:77], v[62:63], v[62:63]
	v_add_f32_e32 v61, v75, v61
	v_and_b32_e32 v52, 0xffff0000, v47
	v_lshlrev_b32_e32 v53, 16, v47
	v_add_f32_e32 v61, v76, v61
	v_pk_mul_f32 v[46:47], v[52:53], v[52:53]
	v_add_f32_e32 v61, v77, v61
	v_add_f32_e32 v47, v47, v61
	v_add_f32_e32 v46, v46, v47
	s_nop 1
	v_mov_b32_dpp v47, v46 quad_perm:[1,0,3,2] row_mask:0xf bank_mask:0xf
	v_lshrrev_b32_e32 v61, 31, v35
	v_ashrrev_i32_e32 v35, 11, v35
	v_add_u32_e32 v35, v35, v61
	v_mul_i32_i24_e32 v35, 0x1100, v35
	v_add_f32_e32 v46, v46, v47
	s_nop 1
	v_mov_b32_dpp v47, v46 quad_perm:[2,3,0,1] row_mask:0xf bank_mask:0xf
	v_sub_u32_e32 v35, v34, v35
	v_add_u32_e32 v61, 0xffffff00, v35
	v_cmp_lt_i32_e64 s[42:43], s6, v35
	v_and_b32_e32 v35, 63, v35
	v_add_f32_e32 v46, v46, v47
	v_fmamk_f32 v46, v46, 0x3c800000, v234
	v_mul_f32_e32 v47, 0x4b800000, v46
	v_cmp_gt_f32_e64 s[44:45], s90, v46
	s_nop 1
	v_cndmask_b32_e64 v46, v46, v47, s[44:45]
	v_rsq_f32_e32 v46, v46
	v_ashrrev_i32_e32 v47, 6, v61
	v_cndmask_b32_e32 v35, v35, v47, vcc
	v_lshlrev_b32_e32 v35, 4, v35
	v_mul_f32_e32 v47, 0x45800000, v46
	v_cndmask_b32_e64 v46, v46, v47, s[44:45]
	v_pk_mul_f32 v[54:55], v[46:47], v[54:55] op_sel_hi:[0,1]
	v_pk_mul_f32 v[48:49], v[46:47], v[48:49] op_sel_hi:[0,1]
	v_pk_mul_f32 v[64:65], v[46:47], v[56:57] op_sel_hi:[0,1]
	v_pk_mul_f32 v[50:51], v[46:47], v[50:51] op_sel_hi:[0,1]
	v_pk_mul_f32 v[66:67], v[46:47], v[58:59] op_sel_hi:[0,1]
	v_pk_mul_f32 v[44:45], v[46:47], v[44:45] op_sel_hi:[0,1]
	v_pk_mul_f32 v[62:63], v[46:47], v[62:63] op_sel_hi:[0,1]
	v_pk_mul_f32 v[68:69], v[46:47], v[52:53] op_sel_hi:[0,1]
	v_pk_mul_f32 v[58:59], v[30:31], v[54:55]
	v_pk_mul_f32 v[56:57], v[32:33], v[48:49]
	v_pk_mul_f32 v[54:55], v[26:27], v[64:65]
	v_pk_mul_f32 v[52:53], v[28:29], v[50:51]
	v_pk_mul_f32 v[50:51], v[22:23], v[66:67]
	v_pk_mul_f32 v[48:49], v[24:25], v[44:45]
	v_pk_mul_f32 v[46:47], v[18:19], v[62:63]
	v_pk_mul_f32 v[44:45], v[20:21], v[68:69] op_sel:[0,1] op_sel_hi:[1,0]
	v_lshl_add_u32 v35, v35, 2, 0
	s_and_saveexec_b64 s[14:15], s[42:43]
	s_cbranch_execz .Lqk_join_1
	v_mov_b32_dpp v82, v58 quad_perm:[1,0,3,2] row_mask:0xf bank_mask:0xf
	v_mov_b32_dpp v83, v59 quad_perm:[1,0,3,2] row_mask:0xf bank_mask:0xf
	ds_read_b128 v[62:65], v35
	ds_read_b128 v[66:69], v35 offset:16
	ds_read_b128 v[70:73], v35 offset:32
	ds_read_b128 v[74:77], v35 offset:48
	ds_read_b128 v[78:81], v35 offset:4096
	v_mov_b32_dpp v86, v54 quad_perm:[1,0,3,2] row_mask:0xf bank_mask:0xf
	v_mov_b32_dpp v87, v55 quad_perm:[1,0,3,2] row_mask:0xf bank_mask:0xf
	v_mov_b32_dpp v90, v50 quad_perm:[1,0,3,2] row_mask:0xf bank_mask:0xf
	v_mov_b32_dpp v91, v51 quad_perm:[1,0,3,2] row_mask:0xf bank_mask:0xf
	s_waitcnt lgkmcnt(0)
	v_pk_mul_f32 v[82:83], v[78:79], v[82:83]
	v_mov_b32_dpp v78, v56 quad_perm:[1,0,3,2] row_mask:0xf bank_mask:0xf
	v_mov_b32_dpp v79, v57 quad_perm:[1,0,3,2] row_mask:0xf bank_mask:0xf
	v_mov_b32_dpp v94, v46 quad_perm:[1,0,3,2] row_mask:0xf bank_mask:0xf
	v_mov_b32_dpp v95, v47 quad_perm:[1,0,3,2] row_mask:0xf bank_mask:0xf
	v_cndmask_b32_e64 v83, v83, -v83, s[40:41]
	v_cndmask_b32_e64 v82, v82, -v82, s[40:41]
	v_pk_mul_f32 v[84:85], v[80:81], v[78:79]
	ds_read_b128 v[78:81], v35 offset:4112
	v_cndmask_b32_e64 v85, v85, -v85, s[40:41]
	v_cndmask_b32_e64 v84, v84, -v84, s[40:41]
	v_pk_fma_f32 v[56:57], v[56:57], v[64:65], v[84:85]
	v_pk_fma_f32 v[58:59], v[58:59], v[62:63], v[82:83]
	s_waitcnt lgkmcnt(0)
	v_pk_mul_f32 v[86:87], v[78:79], v[86:87]
	v_mov_b32_dpp v78, v52 quad_perm:[1,0,3,2] row_mask:0xf bank_mask:0xf
	v_mov_b32_dpp v79, v53 quad_perm:[1,0,3,2] row_mask:0xf bank_mask:0xf
	v_cndmask_b32_e64 v87, v87, -v87, s[40:41]
	v_cndmask_b32_e64 v86, v86, -v86, s[40:41]
	v_pk_fma_f32 v[54:55], v[54:55], v[66:67], v[86:87]
	v_pk_mul_f32 v[88:89], v[80:81], v[78:79]
	ds_read_b128 v[78:81], v35 offset:4128
	v_cndmask_b32_e64 v88, v88, -v88, s[40:41]
	v_cndmask_b32_e64 v89, v89, -v89, s[40:41]
	v_pk_fma_f32 v[52:53], v[52:53], v[68:69], v[88:89]
	s_waitcnt lgkmcnt(0)
	v_pk_mul_f32 v[90:91], v[78:79], v[90:91]
	v_mov_b32_dpp v78, v48 quad_perm:[1,0,3,2] row_mask:0xf bank_mask:0xf
	v_mov_b32_dpp v79, v49 quad_perm:[1,0,3,2] row_mask:0xf bank_mask:0xf
	v_cndmask_b32_e64 v90, v90, -v90, s[40:41]
	v_cndmask_b32_e64 v91, v91, -v91, s[40:41]
	v_pk_fma_f32 v[50:51], v[50:51], v[70:71], v[90:91]
	v_pk_mul_f32 v[92:93], v[80:81], v[78:79]
	ds_read_b128 v[78:81], v35 offset:4144
	v_cndmask_b32_e64 v92, v92, -v92, s[40:41]
	v_cndmask_b32_e64 v93, v93, -v93, s[40:41]
	v_pk_fma_f32 v[48:49], v[48:49], v[72:73], v[92:93]
	s_waitcnt lgkmcnt(0)
	v_pk_mul_f32 v[78:79], v[78:79], v[94:95]
	v_mov_b32_dpp v94, v44 quad_perm:[1,0,3,2] row_mask:0xf bank_mask:0xf
	v_mov_b32_dpp v95, v45 quad_perm:[1,0,3,2] row_mask:0xf bank_mask:0xf
	v_cndmask_b32_e64 v78, v78, -v78, s[40:41]
	v_cndmask_b32_e64 v79, v79, -v79, s[40:41]
	v_pk_fma_f32 v[46:47], v[46:47], v[74:75], v[78:79]
	v_pk_mul_f32 v[80:81], v[80:81], v[94:95]
	s_nop 0
	v_cndmask_b32_e64 v80, v80, -v80, s[40:41]
	v_cndmask_b32_e64 v81, v81, -v81, s[40:41]
	v_pk_fma_f32 v[44:45], v[44:45], v[76:77], v[80:81]
.Lqk_join_1:
	s_or_b64 exec, exec, s[14:15]
	v_mul_f32_e32 v50, 0x3e38aa3b, v50
	v_mul_f32_e32 v47, 0x3e38aa3b, v47
	v_mul_f32_e32 v58, 0x3e38aa3b, v58
	v_mul_f32_e32 v59, 0x3e38aa3b, v59
	v_mul_f32_e32 v56, 0x3e38aa3b, v56
	v_mul_f32_e32 v57, 0x3e38aa3b, v57
	v_mul_f32_e32 v54, 0x3e38aa3b, v54
	v_mul_f32_e32 v55, 0x3e38aa3b, v55
	v_mul_f32_e32 v52, 0x3e38aa3b, v52
	v_mul_f32_e32 v53, 0x3e38aa3b, v53
	v_mul_f32_e32 v51, 0x3e38aa3b, v51
	v_mul_f32_e32 v61, 0x3e38aa3b, v48
	v_mul_f32_e32 v49, 0x3e38aa3b, v49
	v_mul_f32_e32 v62, 0x3e38aa3b, v46
	v_mul_f32_e32 v63, 0x3e38aa3b, v44
	v_mul_f32_e32 v64, 0x3e38aa3b, v45
	s_nop 1
	v_cvt_pk_bf16_f32 v44, v58, v59
	s_nop 1
	v_cvt_pk_bf16_f32 v48, v50, v51
	s_nop 1
	v_cvt_pk_bf16_f32 v45, v56, v57
	s_nop 1
	v_cvt_pk_bf16_f32 v46, v54, v55
	s_nop 1
	v_cvt_pk_bf16_f32 v50, v62, v47
	s_nop 1
	v_cvt_pk_bf16_f32 v47, v52, v53
	s_nop 1
	v_cvt_pk_bf16_f32 v49, v61, v49
	s_nop 1
	v_cvt_pk_bf16_f32 v51, v63, v64
	global_store_dwordx4 v[42:43], v[44:47], off
	global_store_dwordx4 v[42:43], v[48:51], off offset:16
	v_lshl_add_u64 v[40:41], v[38:39], 0, v[40:41]
	s_waitcnt vmcnt(22)
	s_nop 1
	v_mov_b32_e32 v42, v124
	v_mov_b32_e32 v43, v125
	v_mov_b32_e32 v44, v126
	v_mov_b32_e32 v45, v127
	v_mov_b32_e32 v46, v128
	v_mov_b32_e32 v47, v129
	v_mov_b32_e32 v48, v130
	v_mov_b32_e32 v49, v131
	v_lshl_add_u64 v[96:97], s[100:101], 0, v[40:41]
	global_load_dwordx4 v[124:127], v[96:97], off offset:16
	global_load_dwordx4 v[128:131], v[96:97], off
	v_lshlrev_b32_e32 v68, 16, v42
	v_lshlrev_b32_e32 v52, 16, v46
	v_and_b32_e32 v53, 0xffff0000, v46
	v_pk_mul_f32 v[54:55], v[52:53], v[52:53]
	v_lshlrev_b32_e32 v46, 16, v47
	v_and_b32_e32 v47, 0xffff0000, v47
	v_pk_mul_f32 v[58:59], v[46:47], v[46:47]
	v_add_f32_e32 v54, v54, v55
	v_lshlrev_b32_e32 v62, 16, v48
	v_and_b32_e32 v63, 0xffff0000, v48
	v_add_f32_e32 v54, v58, v54
	v_pk_mul_f32 v[64:65], v[62:63], v[62:63]
	v_add_f32_e32 v54, v59, v54
	v_lshlrev_b32_e32 v48, 16, v49
	v_and_b32_e32 v49, 0xffff0000, v49
	v_add_f32_e32 v54, v64, v54
	v_pk_mul_f32 v[66:67], v[48:49], v[48:49]
	v_add_f32_e32 v54, v65, v54
	v_and_b32_e32 v69, 0xffff0000, v42
	v_add_f32_e32 v54, v66, v54
	v_pk_mul_f32 v[70:71], v[68:69], v[68:69]
	v_add_f32_e32 v54, v67, v54
	v_lshlrev_b32_e32 v72, 16, v43
	v_and_b32_e32 v73, 0xffff0000, v43
	v_add_f32_e32 v54, v70, v54
	v_pk_mul_f32 v[42:43], v[72:73], v[72:73]
	v_add_f32_e32 v54, v71, v54
	v_lshlrev_b32_e32 v74, 16, v44
	v_and_b32_e32 v75, 0xffff0000, v44
	v_add_f32_e32 v42, v42, v54
	v_and_b32_e32 v56, 0xffff0000, v45
	v_lshlrev_b32_e32 v57, 16, v45
	v_pk_mul_f32 v[44:45], v[74:75], v[74:75]
	v_add_f32_e32 v42, v43, v42
	v_add_f32_e32 v42, v44, v42
	v_pk_mul_f32 v[50:51], v[56:57], v[56:57]
	v_add_f32_e32 v42, v45, v42
	v_add_f32_e32 v42, v51, v42
	v_add_f32_e32 v42, v50, v42
	s_nop 1
	v_mov_b32_dpp v43, v42 quad_perm:[1,0,3,2] row_mask:0xf bank_mask:0xf
	v_add_f32_e32 v42, v42, v43
	s_nop 1
	v_mov_b32_dpp v43, v42 quad_perm:[2,3,0,1] row_mask:0xf bank_mask:0xf
	v_add_f32_e32 v42, v42, v43
	v_fmamk_f32 v42, v42, 0x3c800000, v234
	v_cmp_gt_f32_e64 s[44:45], s90, v42
	v_mul_f32_e32 v43, 0x4b800000, v42
	s_nop 0
	v_cndmask_b32_e64 v42, v42, v43, s[44:45]
	v_rsq_f32_e32 v42, v42
	s_nop 0
	v_mul_f32_e32 v43, 0x45800000, v42
	v_cndmask_b32_e64 v58, v42, v43, s[44:45]
	v_pk_mul_f32 v[42:43], v[58:59], v[52:53] op_sel_hi:[0,1]
	v_pk_mul_f32 v[44:45], v[58:59], v[46:47] op_sel_hi:[0,1]
	v_pk_mul_f32 v[46:47], v[58:59], v[62:63] op_sel_hi:[0,1]
	v_pk_mul_f32 v[48:49], v[58:59], v[48:49] op_sel_hi:[0,1]
	v_pk_mul_f32 v[50:51], v[58:59], v[68:69] op_sel_hi:[0,1]
	v_pk_mul_f32 v[52:53], v[58:59], v[72:73] op_sel_hi:[0,1]
	v_pk_mul_f32 v[54:55], v[58:59], v[74:75] op_sel_hi:[0,1]
	v_pk_mul_f32 v[56:57], v[58:59], v[56:57] op_sel_hi:[0,1]
	v_pk_mul_f32 v[42:43], v[14:15], v[42:43]
	v_pk_mul_f32 v[44:45], v[16:17], v[44:45]
	v_pk_mul_f32 v[46:47], v[10:11], v[46:47]
	v_pk_mul_f32 v[48:49], v[12:13], v[48:49]
	v_pk_mul_f32 v[50:51], v[6:7], v[50:51]
	v_pk_mul_f32 v[52:53], v[8:9], v[52:53]
	v_pk_mul_f32 v[54:55], v[2:3], v[54:55]
	v_pk_mul_f32 v[56:57], v[4:5], v[56:57] op_sel:[0,1] op_sel_hi:[1,0]
	s_and_saveexec_b64 s[14:15], s[42:43]
	s_cbranch_execz .Lqk_tail_1
	v_mov_b32_dpp v58, v42 quad_perm:[1,0,3,2] row_mask:0xf bank_mask:0xf
	v_mov_b32_dpp v59, v43 quad_perm:[1,0,3,2] row_mask:0xf bank_mask:0xf
	ds_read_b128 v[62:65], v35
	ds_read_b128 v[66:69], v35 offset:16
	ds_read_b128 v[70:73], v35 offset:32
	ds_read_b128 v[74:77], v35 offset:48
	ds_read_b128 v[78:81], v35 offset:4096
	v_mov_b32_dpp v84, v46 quad_perm:[1,0,3,2] row_mask:0xf bank_mask:0xf
	v_mov_b32_dpp v85, v47 quad_perm:[1,0,3,2] row_mask:0xf bank_mask:0xf
	v_mov_b32_dpp v88, v50 quad_perm:[1,0,3,2] row_mask:0xf bank_mask:0xf
	v_mov_b32_dpp v89, v51 quad_perm:[1,0,3,2] row_mask:0xf bank_mask:0xf
	s_waitcnt lgkmcnt(0)
	v_pk_mul_f32 v[58:59], v[78:79], v[58:59]
	v_mov_b32_dpp v78, v44 quad_perm:[1,0,3,2] row_mask:0xf bank_mask:0xf
	v_mov_b32_dpp v79, v45 quad_perm:[1,0,3,2] row_mask:0xf bank_mask:0xf
	v_mov_b32_dpp v92, v54 quad_perm:[1,0,3,2] row_mask:0xf bank_mask:0xf
	v_mov_b32_dpp v93, v55 quad_perm:[1,0,3,2] row_mask:0xf bank_mask:0xf
	v_cndmask_b32_e64 v59, v59, -v59, s[40:41]
	v_cndmask_b32_e64 v58, v58, -v58, s[40:41]
	v_pk_mul_f32 v[82:83], v[80:81], v[78:79]
	ds_read_b128 v[78:81], v35 offset:4112
	v_cndmask_b32_e64 v83, v83, -v83, s[40:41]
	v_cndmask_b32_e64 v82, v82, -v82, s[40:41]
	v_pk_fma_f32 v[44:45], v[44:45], v[64:65], v[82:83]
	v_pk_fma_f32 v[42:43], v[42:43], v[62:63], v[58:59]
	s_waitcnt lgkmcnt(0)
	v_pk_mul_f32 v[84:85], v[78:79], v[84:85]
	v_mov_b32_dpp v78, v48 quad_perm:[1,0,3,2] row_mask:0xf bank_mask:0xf
	v_mov_b32_dpp v79, v49 quad_perm:[1,0,3,2] row_mask:0xf bank_mask:0xf
	v_cndmask_b32_e64 v85, v85, -v85, s[40:41]
	v_cndmask_b32_e64 v84, v84, -v84, s[40:41]
	v_pk_fma_f32 v[46:47], v[46:47], v[66:67], v[84:85]
	v_pk_mul_f32 v[86:87], v[80:81], v[78:79]
	ds_read_b128 v[78:81], v35 offset:4128
	v_cndmask_b32_e64 v86, v86, -v86, s[40:41]
	v_cndmask_b32_e64 v87, v87, -v87, s[40:41]
	v_pk_fma_f32 v[48:49], v[48:49], v[68:69], v[86:87]
	s_waitcnt lgkmcnt(0)
	v_pk_mul_f32 v[88:89], v[78:79], v[88:89]
	v_mov_b32_dpp v78, v52 quad_perm:[1,0,3,2] row_mask:0xf bank_mask:0xf
	v_mov_b32_dpp v79, v53 quad_perm:[1,0,3,2] row_mask:0xf bank_mask:0xf
	v_cndmask_b32_e64 v88, v88, -v88, s[40:41]
	v_cndmask_b32_e64 v89, v89, -v89, s[40:41]
	v_pk_fma_f32 v[50:51], v[50:51], v[70:71], v[88:89]
	v_pk_mul_f32 v[90:91], v[80:81], v[78:79]
	ds_read_b128 v[78:81], v35 offset:4144
	v_cndmask_b32_e64 v90, v90, -v90, s[40:41]
	v_cndmask_b32_e64 v91, v91, -v91, s[40:41]
	v_pk_fma_f32 v[52:53], v[52:53], v[72:73], v[90:91]
	s_waitcnt lgkmcnt(0)
	v_pk_mul_f32 v[78:79], v[78:79], v[92:93]
	v_mov_b32_dpp v92, v56 quad_perm:[1,0,3,2] row_mask:0xf bank_mask:0xf
	v_mov_b32_dpp v93, v57 quad_perm:[1,0,3,2] row_mask:0xf bank_mask:0xf
	v_cndmask_b32_e64 v78, v78, -v78, s[40:41]
	v_cndmask_b32_e64 v79, v79, -v79, s[40:41]
	v_pk_fma_f32 v[54:55], v[54:55], v[74:75], v[78:79]
	v_pk_mul_f32 v[80:81], v[80:81], v[92:93]
	s_nop 0
	v_cndmask_b32_e64 v80, v80, -v80, s[40:41]
	v_cndmask_b32_e64 v81, v81, -v81, s[40:41]
	v_pk_fma_f32 v[56:57], v[56:57], v[76:77], v[80:81]

.Lqk_head_2:
	v_ashrrev_i32_e32 v35, 31, v34
	v_lshlrev_b64 v[40:41], 11, v[34:35]
	v_lshl_add_u64 v[42:43], v[36:37], 0, v[40:41]
	s_waitcnt vmcnt(22)
	v_mov_b32_e32 v44, v132
	v_mov_b32_e32 v45, v133
	v_mov_b32_e32 v46, v134
	v_mov_b32_e32 v47, v135
	v_mov_b32_e32 v48, v136
	v_mov_b32_e32 v49, v137
	v_mov_b32_e32 v50, v138
	v_mov_b32_e32 v51, v139
	v_lshl_add_u64 v[96:97], s[100:101], 0, v[42:43]
	global_load_dwordx4 v[132:135], v[96:97], off offset:16
	global_load_dwordx4 v[136:139], v[96:97], off
	s_mov_b32 s6, 0x78787879
	v_mul_hi_i32 v35, v34, s6
	s_movk_i32 s6, 0xff
	v_lshlrev_b32_e32 v58, 16, v44
	v_lshlrev_b32_e32 v54, 16, v48
	v_and_b32_e32 v55, 0xffff0000, v48
	v_lshlrev_b32_e32 v48, 16, v49
	v_and_b32_e32 v49, 0xffff0000, v49
	v_pk_mul_f32 v[64:65], v[54:55], v[54:55]
	v_pk_mul_f32 v[66:67], v[48:49], v[48:49]
	v_add_f32_e32 v61, v64, v65
	v_lshlrev_b32_e32 v56, 16, v50
	v_and_b32_e32 v57, 0xffff0000, v50
	v_add_f32_e32 v61, v66, v61
	v_pk_mul_f32 v[68:69], v[56:57], v[56:57]
	v_add_f32_e32 v61, v67, v61
	v_lshlrev_b32_e32 v50, 16, v51
	v_and_b32_e32 v51, 0xffff0000, v51
	v_add_f32_e32 v61, v68, v61
	v_pk_mul_f32 v[70:71], v[50:51], v[50:51]
	v_add_f32_e32 v61, v69, v61
	v_and_b32_e32 v59, 0xffff0000, v44
	v_add_f32_e32 v61, v70, v61
	v_pk_mul_f32 v[72:73], v[58:59], v[58:59]
	v_add_f32_e32 v61, v71, v61
	v_lshlrev_b32_e32 v44, 16, v45
	v_and_b32_e32 v45, 0xffff0000, v45
	v_add_f32_e32 v61, v72, v61
	v_pk_mul_f32 v[74:75], v[44:45], v[44:45]
	v_add_f32_e32 v61, v73, v61
	v_lshlrev_b32_e32 v62, 16, v46
	v_and_b32_e32 v63, 0xffff0000, v46
	v_add_f32_e32 v61, v74, v61
	v_pk_mul_f32 v[76:77], v[62:63], v[62:63]
	v_add_f32_e32 v61, v75, v61
	v_and_b32_e32 v52, 0xffff0000, v47
	v_lshlrev_b32_e32 v53, 16, v47
	v_add_f32_e32 v61, v76, v61
	v_pk_mul_f32 v[46:47], v[52:53], v[52:53]
	v_add_f32_e32 v61, v77, v61
	v_add_f32_e32 v47, v47, v61
	v_add_f32_e32 v46, v46, v47
	s_nop 1
	v_mov_b32_dpp v47, v46 quad_perm:[1,0,3,2] row_mask:0xf bank_mask:0xf
	v_lshrrev_b32_e32 v61, 31, v35
	v_ashrrev_i32_e32 v35, 11, v35
	v_add_u32_e32 v35, v35, v61
	v_mul_i32_i24_e32 v35, 0x1100, v35
	v_add_f32_e32 v46, v46, v47
	s_nop 1
	v_mov_b32_dpp v47, v46 quad_perm:[2,3,0,1] row_mask:0xf bank_mask:0xf
	v_sub_u32_e32 v35, v34, v35
	v_add_u32_e32 v61, 0xffffff00, v35
	v_cmp_lt_i32_e64 s[42:43], s6, v35
	v_and_b32_e32 v35, 63, v35
	v_add_f32_e32 v46, v46, v47
	v_fmamk_f32 v46, v46, 0x3c800000, v234
	v_mul_f32_e32 v47, 0x4b800000, v46
	v_cmp_gt_f32_e64 s[44:45], s90, v46
	s_nop 1
	v_cndmask_b32_e64 v46, v46, v47, s[44:45]
	v_rsq_f32_e32 v46, v46
	v_ashrrev_i32_e32 v47, 6, v61
	v_cndmask_b32_e32 v35, v35, v47, vcc
	v_lshlrev_b32_e32 v35, 4, v35
	v_mul_f32_e32 v47, 0x45800000, v46
	v_cndmask_b32_e64 v46, v46, v47, s[44:45]
	v_pk_mul_f32 v[54:55], v[46:47], v[54:55] op_sel_hi:[0,1]
	v_pk_mul_f32 v[48:49], v[46:47], v[48:49] op_sel_hi:[0,1]
	v_pk_mul_f32 v[64:65], v[46:47], v[56:57] op_sel_hi:[0,1]
	v_pk_mul_f32 v[50:51], v[46:47], v[50:51] op_sel_hi:[0,1]
	v_pk_mul_f32 v[66:67], v[46:47], v[58:59] op_sel_hi:[0,1]
	v_pk_mul_f32 v[44:45], v[46:47], v[44:45] op_sel_hi:[0,1]
	v_pk_mul_f32 v[62:63], v[46:47], v[62:63] op_sel_hi:[0,1]
	v_pk_mul_f32 v[68:69], v[46:47], v[52:53] op_sel_hi:[0,1]
	v_pk_mul_f32 v[58:59], v[30:31], v[54:55]
	v_pk_mul_f32 v[56:57], v[32:33], v[48:49]
	v_pk_mul_f32 v[54:55], v[26:27], v[64:65]
	v_pk_mul_f32 v[52:53], v[28:29], v[50:51]
	v_pk_mul_f32 v[50:51], v[22:23], v[66:67]
	v_pk_mul_f32 v[48:49], v[24:25], v[44:45]
	v_pk_mul_f32 v[46:47], v[18:19], v[62:63]
	v_pk_mul_f32 v[44:45], v[20:21], v[68:69] op_sel:[0,1] op_sel_hi:[1,0]
	v_lshl_add_u32 v35, v35, 2, 0
	s_and_saveexec_b64 s[14:15], s[42:43]
	s_cbranch_execz .Lqk_join_2
	v_mov_b32_dpp v82, v58 quad_perm:[1,0,3,2] row_mask:0xf bank_mask:0xf
	v_mov_b32_dpp v83, v59 quad_perm:[1,0,3,2] row_mask:0xf bank_mask:0xf
	ds_read_b128 v[62:65], v35
	ds_read_b128 v[66:69], v35 offset:16
	ds_read_b128 v[70:73], v35 offset:32
	ds_read_b128 v[74:77], v35 offset:48
	ds_read_b128 v[78:81], v35 offset:4096
	v_mov_b32_dpp v86, v54 quad_perm:[1,0,3,2] row_mask:0xf bank_mask:0xf
	v_mov_b32_dpp v87, v55 quad_perm:[1,0,3,2] row_mask:0xf bank_mask:0xf
	v_mov_b32_dpp v90, v50 quad_perm:[1,0,3,2] row_mask:0xf bank_mask:0xf
	v_mov_b32_dpp v91, v51 quad_perm:[1,0,3,2] row_mask:0xf bank_mask:0xf
	s_waitcnt lgkmcnt(0)
	v_pk_mul_f32 v[82:83], v[78:79], v[82:83]
	v_mov_b32_dpp v78, v56 quad_perm:[1,0,3,2] row_mask:0xf bank_mask:0xf
	v_mov_b32_dpp v79, v57 quad_perm:[1,0,3,2] row_mask:0xf bank_mask:0xf
	v_mov_b32_dpp v94, v46 quad_perm:[1,0,3,2] row_mask:0xf bank_mask:0xf
	v_mov_b32_dpp v95, v47 quad_perm:[1,0,3,2] row_mask:0xf bank_mask:0xf
	v_cndmask_b32_e64 v83, v83, -v83, s[40:41]
	v_cndmask_b32_e64 v82, v82, -v82, s[40:41]
	v_pk_mul_f32 v[84:85], v[80:81], v[78:79]
	ds_read_b128 v[78:81], v35 offset:4112
	v_cndmask_b32_e64 v85, v85, -v85, s[40:41]
	v_cndmask_b32_e64 v84, v84, -v84, s[40:41]
	v_pk_fma_f32 v[56:57], v[56:57], v[64:65], v[84:85]
	v_pk_fma_f32 v[58:59], v[58:59], v[62:63], v[82:83]
	s_waitcnt lgkmcnt(0)
	v_pk_mul_f32 v[86:87], v[78:79], v[86:87]
	v_mov_b32_dpp v78, v52 quad_perm:[1,0,3,2] row_mask:0xf bank_mask:0xf
	v_mov_b32_dpp v79, v53 quad_perm:[1,0,3,2] row_mask:0xf bank_mask:0xf
	v_cndmask_b32_e64 v87, v87, -v87, s[40:41]
	v_cndmask_b32_e64 v86, v86, -v86, s[40:41]
	v_pk_fma_f32 v[54:55], v[54:55], v[66:67], v[86:87]
	v_pk_mul_f32 v[88:89], v[80:81], v[78:79]
	ds_read_b128 v[78:81], v35 offset:4128
	v_cndmask_b32_e64 v88, v88, -v88, s[40:41]
	v_cndmask_b32_e64 v89, v89, -v89, s[40:41]
	v_pk_fma_f32 v[52:53], v[52:53], v[68:69], v[88:89]
	s_waitcnt lgkmcnt(0)
	v_pk_mul_f32 v[90:91], v[78:79], v[90:91]
	v_mov_b32_dpp v78, v48 quad_perm:[1,0,3,2] row_mask:0xf bank_mask:0xf
	v_mov_b32_dpp v79, v49 quad_perm:[1,0,3,2] row_mask:0xf bank_mask:0xf
	v_cndmask_b32_e64 v90, v90, -v90, s[40:41]
	v_cndmask_b32_e64 v91, v91, -v91, s[40:41]
	v_pk_fma_f32 v[50:51], v[50:51], v[70:71], v[90:91]
	v_pk_mul_f32 v[92:93], v[80:81], v[78:79]
	ds_read_b128 v[78:81], v35 offset:4144
	v_cndmask_b32_e64 v92, v92, -v92, s[40:41]
	v_cndmask_b32_e64 v93, v93, -v93, s[40:41]
	v_pk_fma_f32 v[48:49], v[48:49], v[72:73], v[92:93]
	s_waitcnt lgkmcnt(0)
	v_pk_mul_f32 v[78:79], v[78:79], v[94:95]
	v_mov_b32_dpp v94, v44 quad_perm:[1,0,3,2] row_mask:0xf bank_mask:0xf
	v_mov_b32_dpp v95, v45 quad_perm:[1,0,3,2] row_mask:0xf bank_mask:0xf
	v_cndmask_b32_e64 v78, v78, -v78, s[40:41]
	v_cndmask_b32_e64 v79, v79, -v79, s[40:41]
	v_pk_fma_f32 v[46:47], v[46:47], v[74:75], v[78:79]
	v_pk_mul_f32 v[80:81], v[80:81], v[94:95]
	s_nop 0
	v_cndmask_b32_e64 v80, v80, -v80, s[40:41]
	v_cndmask_b32_e64 v81, v81, -v81, s[40:41]
	v_pk_fma_f32 v[44:45], v[44:45], v[76:77], v[80:81]
.Lqk_join_2:
	s_or_b64 exec, exec, s[14:15]
	v_mul_f32_e32 v50, 0x3e38aa3b, v50
	v_mul_f32_e32 v47, 0x3e38aa3b, v47
	v_mul_f32_e32 v58, 0x3e38aa3b, v58
	v_mul_f32_e32 v59, 0x3e38aa3b, v59
	v_mul_f32_e32 v56, 0x3e38aa3b, v56
	v_mul_f32_e32 v57, 0x3e38aa3b, v57
	v_mul_f32_e32 v54, 0x3e38aa3b, v54
	v_mul_f32_e32 v55, 0x3e38aa3b, v55
	v_mul_f32_e32 v52, 0x3e38aa3b, v52
	v_mul_f32_e32 v53, 0x3e38aa3b, v53
	v_mul_f32_e32 v51, 0x3e38aa3b, v51
	v_mul_f32_e32 v61, 0x3e38aa3b, v48
	v_mul_f32_e32 v49, 0x3e38aa3b, v49
	v_mul_f32_e32 v62, 0x3e38aa3b, v46
	v_mul_f32_e32 v63, 0x3e38aa3b, v44
	v_mul_f32_e32 v64, 0x3e38aa3b, v45
	s_nop 1
	v_cvt_pk_bf16_f32 v44, v58, v59
	s_nop 1
	v_cvt_pk_bf16_f32 v48, v50, v51
	s_nop 1
	v_cvt_pk_bf16_f32 v45, v56, v57
	s_nop 1
	v_cvt_pk_bf16_f32 v46, v54, v55
	s_nop 1
	v_cvt_pk_bf16_f32 v50, v62, v47
	s_nop 1
	v_cvt_pk_bf16_f32 v47, v52, v53
	s_nop 1
	v_cvt_pk_bf16_f32 v49, v61, v49
	s_nop 1
	v_cvt_pk_bf16_f32 v51, v63, v64
	global_store_dwordx4 v[42:43], v[44:47], off
	global_store_dwordx4 v[42:43], v[48:51], off offset:16
	v_lshl_add_u64 v[40:41], v[38:39], 0, v[40:41]
	s_waitcnt vmcnt(22)
	s_nop 1
	v_mov_b32_e32 v42, v140
	v_mov_b32_e32 v43, v141
	v_mov_b32_e32 v44, v142
	v_mov_b32_e32 v45, v143
	v_mov_b32_e32 v46, v144
	v_mov_b32_e32 v47, v145
	v_mov_b32_e32 v48, v146
	v_mov_b32_e32 v49, v147
	v_lshl_add_u64 v[96:97], s[100:101], 0, v[40:41]
	global_load_dwordx4 v[140:143], v[96:97], off offset:16
	global_load_dwordx4 v[144:147], v[96:97], off
	v_lshlrev_b32_e32 v68, 16, v42
	v_lshlrev_b32_e32 v52, 16, v46
	v_and_b32_e32 v53, 0xffff0000, v46
	v_pk_mul_f32 v[54:55], v[52:53], v[52:53]
	v_lshlrev_b32_e32 v46, 16, v47
	v_and_b32_e32 v47, 0xffff0000, v47
	v_pk_mul_f32 v[58:59], v[46:47], v[46:47]
	v_add_f32_e32 v54, v54, v55
	v_lshlrev_b32_e32 v62, 16, v48
	v_and_b32_e32 v63, 0xffff0000, v48
	v_add_f32_e32 v54, v58, v54
	v_pk_mul_f32 v[64:65], v[62:63], v[62:63]
	v_add_f32_e32 v54, v59, v54
	v_lshlrev_b32_e32 v48, 16, v49
	v_and_b32_e32 v49, 0xffff0000, v49
	v_add_f32_e32 v54, v64, v54
	v_pk_mul_f32 v[66:67], v[48:49], v[48:49]
	v_add_f32_e32 v54, v65, v54
	v_and_b32_e32 v69, 0xffff0000, v42
	v_add_f32_e32 v54, v66, v54
	v_pk_mul_f32 v[70:71], v[68:69], v[68:69]
	v_add_f32_e32 v54, v67, v54
	v_lshlrev_b32_e32 v72, 16, v43
	v_and_b32_e32 v73, 0xffff0000, v43
	v_add_f32_e32 v54, v70, v54
	v_pk_mul_f32 v[42:43], v[72:73], v[72:73]
	v_add_f32_e32 v54, v71, v54
	v_lshlrev_b32_e32 v74, 16, v44
	v_and_b32_e32 v75, 0xffff0000, v44
	v_add_f32_e32 v42, v42, v54
	v_and_b32_e32 v56, 0xffff0000, v45
	v_lshlrev_b32_e32 v57, 16, v45
	v_pk_mul_f32 v[44:45], v[74:75], v[74:75]
	v_add_f32_e32 v42, v43, v42
	v_add_f32_e32 v42, v44, v42
	v_pk_mul_f32 v[50:51], v[56:57], v[56:57]
	v_add_f32_e32 v42, v45, v42
	v_add_f32_e32 v42, v51, v42
	v_add_f32_e32 v42, v50, v42
	s_nop 1
	v_mov_b32_dpp v43, v42 quad_perm:[1,0,3,2] row_mask:0xf bank_mask:0xf
	v_add_f32_e32 v42, v42, v43
	s_nop 1
	v_mov_b32_dpp v43, v42 quad_perm:[2,3,0,1] row_mask:0xf bank_mask:0xf
	v_add_f32_e32 v42, v42, v43
	v_fmamk_f32 v42, v42, 0x3c800000, v234
	v_cmp_gt_f32_e64 s[44:45], s90, v42
	v_mul_f32_e32 v43, 0x4b800000, v42
	s_nop 0
	v_cndmask_b32_e64 v42, v42, v43, s[44:45]
	v_rsq_f32_e32 v42, v42
	s_nop 0
	v_mul_f32_e32 v43, 0x45800000, v42
	v_cndmask_b32_e64 v58, v42, v43, s[44:45]
	v_pk_mul_f32 v[42:43], v[58:59], v[52:53] op_sel_hi:[0,1]
	v_pk_mul_f32 v[44:45], v[58:59], v[46:47] op_sel_hi:[0,1]
	v_pk_mul_f32 v[46:47], v[58:59], v[62:63] op_sel_hi:[0,1]
	v_pk_mul_f32 v[48:49], v[58:59], v[48:49] op_sel_hi:[0,1]
	v_pk_mul_f32 v[50:51], v[58:59], v[68:69] op_sel_hi:[0,1]
	v_pk_mul_f32 v[52:53], v[58:59], v[72:73] op_sel_hi:[0,1]
	v_pk_mul_f32 v[54:55], v[58:59], v[74:75] op_sel_hi:[0,1]
	v_pk_mul_f32 v[56:57], v[58:59], v[56:57] op_sel_hi:[0,1]
	v_pk_mul_f32 v[42:43], v[14:15], v[42:43]
	v_pk_mul_f32 v[44:45], v[16:17], v[44:45]
	v_pk_mul_f32 v[46:47], v[10:11], v[46:47]
	v_pk_mul_f32 v[48:49], v[12:13], v[48:49]
	v_pk_mul_f32 v[50:51], v[6:7], v[50:51]
	v_pk_mul_f32 v[52:53], v[8:9], v[52:53]
	v_pk_mul_f32 v[54:55], v[2:3], v[54:55]
	v_pk_mul_f32 v[56:57], v[4:5], v[56:57] op_sel:[0,1] op_sel_hi:[1,0]
	s_and_saveexec_b64 s[14:15], s[42:43]
	s_cbranch_execz .Lqk_tail_2
	v_mov_b32_dpp v58, v42 quad_perm:[1,0,3,2] row_mask:0xf bank_mask:0xf
	v_mov_b32_dpp v59, v43 quad_perm:[1,0,3,2] row_mask:0xf bank_mask:0xf
	ds_read_b128 v[62:65], v35
	ds_read_b128 v[66:69], v35 offset:16
	ds_read_b128 v[70:73], v35 offset:32
	ds_read_b128 v[74:77], v35 offset:48
	ds_read_b128 v[78:81], v35 offset:4096
	v_mov_b32_dpp v84, v46 quad_perm:[1,0,3,2] row_mask:0xf bank_mask:0xf
	v_mov_b32_dpp v85, v47 quad_perm:[1,0,3,2] row_mask:0xf bank_mask:0xf
	v_mov_b32_dpp v88, v50 quad_perm:[1,0,3,2] row_mask:0xf bank_mask:0xf
	v_mov_b32_dpp v89, v51 quad_perm:[1,0,3,2] row_mask:0xf bank_mask:0xf
	s_waitcnt lgkmcnt(0)
	v_pk_mul_f32 v[58:59], v[78:79], v[58:59]
	v_mov_b32_dpp v78, v44 quad_perm:[1,0,3,2] row_mask:0xf bank_mask:0xf
	v_mov_b32_dpp v79, v45 quad_perm:[1,0,3,2] row_mask:0xf bank_mask:0xf
	v_mov_b32_dpp v92, v54 quad_perm:[1,0,3,2] row_mask:0xf bank_mask:0xf
	v_mov_b32_dpp v93, v55 quad_perm:[1,0,3,2] row_mask:0xf bank_mask:0xf
	v_cndmask_b32_e64 v59, v59, -v59, s[40:41]
	v_cndmask_b32_e64 v58, v58, -v58, s[40:41]
	v_pk_mul_f32 v[82:83], v[80:81], v[78:79]
	ds_read_b128 v[78:81], v35 offset:4112
	v_cndmask_b32_e64 v83, v83, -v83, s[40:41]
	v_cndmask_b32_e64 v82, v82, -v82, s[40:41]
	v_pk_fma_f32 v[44:45], v[44:45], v[64:65], v[82:83]
	v_pk_fma_f32 v[42:43], v[42:43], v[62:63], v[58:59]
	s_waitcnt lgkmcnt(0)
	v_pk_mul_f32 v[84:85], v[78:79], v[84:85]
	v_mov_b32_dpp v78, v48 quad_perm:[1,0,3,2] row_mask:0xf bank_mask:0xf
	v_mov_b32_dpp v79, v49 quad_perm:[1,0,3,2] row_mask:0xf bank_mask:0xf
	v_cndmask_b32_e64 v85, v85, -v85, s[40:41]
	v_cndmask_b32_e64 v84, v84, -v84, s[40:41]
	v_pk_fma_f32 v[46:47], v[46:47], v[66:67], v[84:85]
	v_pk_mul_f32 v[86:87], v[80:81], v[78:79]
	ds_read_b128 v[78:81], v35 offset:4128
	v_cndmask_b32_e64 v86, v86, -v86, s[40:41]
	v_cndmask_b32_e64 v87, v87, -v87, s[40:41]
	v_pk_fma_f32 v[48:49], v[48:49], v[68:69], v[86:87]
	s_waitcnt lgkmcnt(0)
	v_pk_mul_f32 v[88:89], v[78:79], v[88:89]
	v_mov_b32_dpp v78, v52 quad_perm:[1,0,3,2] row_mask:0xf bank_mask:0xf
	v_mov_b32_dpp v79, v53 quad_perm:[1,0,3,2] row_mask:0xf bank_mask:0xf
	v_cndmask_b32_e64 v88, v88, -v88, s[40:41]
	v_cndmask_b32_e64 v89, v89, -v89, s[40:41]
	v_pk_fma_f32 v[50:51], v[50:51], v[70:71], v[88:89]
	v_pk_mul_f32 v[90:91], v[80:81], v[78:79]
	ds_read_b128 v[78:81], v35 offset:4144
	v_cndmask_b32_e64 v90, v90, -v90, s[40:41]
	v_cndmask_b32_e64 v91, v91, -v91, s[40:41]
	v_pk_fma_f32 v[52:53], v[52:53], v[72:73], v[90:91]
	s_waitcnt lgkmcnt(0)
	v_pk_mul_f32 v[78:79], v[78:79], v[92:93]
	v_mov_b32_dpp v92, v56 quad_perm:[1,0,3,2] row_mask:0xf bank_mask:0xf
	v_mov_b32_dpp v93, v57 quad_perm:[1,0,3,2] row_mask:0xf bank_mask:0xf
	v_cndmask_b32_e64 v78, v78, -v78, s[40:41]
	v_cndmask_b32_e64 v79, v79, -v79, s[40:41]
	v_pk_fma_f32 v[54:55], v[54:55], v[74:75], v[78:79]
	v_pk_mul_f32 v[80:81], v[80:81], v[92:93]
	s_nop 0
	v_cndmask_b32_e64 v80, v80, -v80, s[40:41]
	v_cndmask_b32_e64 v81, v81, -v81, s[40:41]
	v_pk_fma_f32 v[56:57], v[56:57], v[76:77], v[80:81]
.Lqk_tail_2:
	s_or_b64 exec, exec, s[14:15]
	v_readlane_b32 s14, v254, 47
	s_movk_i32 s6, 0x43ff
	s_nop 1
	v_cvt_pk_bf16_f32 v42, v42, v43
	s_nop 1
	v_cvt_pk_bf16_f32 v50, v50, v51
	s_nop 1
	v_cvt_pk_bf16_f32 v43, v44, v45
	s_nop 1
	v_cvt_pk_bf16_f32 v51, v52, v53
	s_nop 0
	v_add_u32_e32 v34, s14, v34
	v_cmp_lt_i32_e64 s[42:43], s6, v34
	s_or_b64 s[12:13], s[42:43], s[12:13]
	s_nop 1
	v_cvt_pk_bf16_f32 v44, v46, v47
	s_nop 1
	v_cvt_pk_bf16_f32 v52, v54, v55
	s_nop 1
	v_cvt_pk_bf16_f32 v45, v48, v49
	s_nop 1
	v_cvt_pk_bf16_f32 v53, v56, v57
	global_store_dwordx4 v[40:41], v[42:45], off
	v_readlane_b32 s15, v254, 48
	global_store_dwordx4 v[40:41], v[50:53], off offset:16
	s_andn2_b64 exec, exec, s[12:13]
	s_cbranch_execz .LBB0_392
	s_branch .LBB0_388
